# MoBA gating: k_mean rows staged interleaved in row pairs, hand-written packed-f32 score loop without shuffles, reads for next slice in flight
# speedup vs baseline: 1.0047x; 1.0031x over previous
.LBB0_93:
	s_xor_b64 s[56:57], s[0:1], -1
	s_and_b64 s[0:1], s[0:1], exec
	s_cselect_b32 s8, s43, s44
	s_lshl_b32 s46, s8, 7
	s_ashr_i32 s1, s46, 31
	s_add_u32 s0, s46, s6
	s_addc_u32 s1, s1, 0
	v_lshl_add_u64 v[36:37], s[0:1], 0, v[116:117]
	v_mov_b64_e32 v[40:41], s[88:89]
	v_mad_u64_u32 v[38:39], s[10:11], v36, s72, v[40:41]
	v_mad_i32_i24 v39, v37, s72, v39
	s_lshl_b32 s20, s45, 1
	v_lshl_add_u64 v[36:37], v[38:39], 0, s[20:21]
	v_lshl_add_u64 v[36:37], v[36:37], 0, v[2:3]
	v_add_co_u32_e32 v36, vcc, s3, v36
	s_nop 1
	v_addc_co_u32_e32 v37, vcc, 0, v37, vcc
	global_load_dwordx4 v[4:7], v[36:37], off
	v_lshl_add_u64 v[36:37], s[0:1], 0, v[122:123]
	v_mad_u64_u32 v[38:39], s[10:11], v36, s72, v[40:41]
	v_mad_i32_i24 v39, v37, s72, v39
	v_lshl_add_u64 v[36:37], v[38:39], 0, s[20:21]
	v_lshl_add_u64 v[36:37], v[36:37], 0, v[2:3]
	v_add_co_u32_e32 v36, vcc, s3, v36
	s_nop 1
	v_addc_co_u32_e32 v37, vcc, 0, v37, vcc
	global_load_dwordx4 v[8:11], v[36:37], off
	v_lshl_add_u64 v[36:37], s[0:1], 0, v[124:125]
	v_mad_u64_u32 v[38:39], s[10:11], v36, s72, v[40:41]
	v_mad_i32_i24 v39, v37, s72, v39
	v_lshl_add_u64 v[36:37], v[38:39], 0, s[20:21]
	v_lshl_add_u64 v[36:37], v[36:37], 0, v[2:3]
	v_add_co_u32_e32 v36, vcc, s3, v36
	s_nop 1
	v_addc_co_u32_e32 v37, vcc, 0, v37, vcc
	global_load_dwordx4 v[12:15], v[36:37], off
	v_lshl_add_u64 v[36:37], s[0:1], 0, v[126:127]
	v_mad_u64_u32 v[38:39], s[0:1], v36, s72, v[40:41]
	v_mad_i32_i24 v39, v37, s72, v39
	v_lshl_add_u64 v[36:37], v[38:39], 0, s[20:21]
	v_lshl_add_u64 v[36:37], v[36:37], 0, v[2:3]
	v_add_co_u32_e32 v36, vcc, 0x1000, v36
	s_nop 1
	v_addc_co_u32_e32 v37, vcc, 0, v37, vcc
	global_load_dwordx4 v[16:19], v[36:37], off
	v_lshrrev_b32_e32 v36, 5, v173
	v_lshlrev_b32_e32 v36, 9, v36
	v_mov_b32_e32 v37, 0
	v_lshl_add_u64 v[36:37], v[142:143], 0, v[36:37]
	global_load_dwordx4 v[20:23], v[36:37], off
	global_load_dwordx4 v[24:27], v[36:37], off offset:512
	s_barrier
	v_add_u32_e32 v52, v133, v170
	v_mov_b32_e32 v44, v156
	v_mov_b32_e32 v45, v135
	v_mov_b32_e32 v40, 0
	s_mov_b32 s0, 16
	v_mov_b32_e32 v41, v40
	v_mov_b32_e32 v42, v40
	v_mov_b32_e32 v43, v40
	s_waitcnt vmcnt(5)
	ds_write_b128 v52, v[4:7]
	s_waitcnt vmcnt(4)
	ds_write_b128 v188, v[8:11]
	s_waitcnt vmcnt(3)
	ds_write_b128 v189, v[12:15]
	s_waitcnt vmcnt(2)
	ds_write_b128 v190, v[16:19]
	s_waitcnt vmcnt(0)
	v_lshl_add_u32 v52, v173, 4, v171
	v_mov_b32_e32 v28, v20
	v_mov_b32_e32 v29, v24
	v_mov_b32_e32 v30, v21
	v_mov_b32_e32 v31, v25
	v_mov_b32_e32 v32, v22
	v_mov_b32_e32 v33, v26
	v_mov_b32_e32 v34, v23
	v_mov_b32_e32 v35, v27
	ds_write_b128 v52, v[28:31]
	ds_write_b128 v52, v[32:35] offset:16
	v_mov_b32_e32 v38, v40
	v_mov_b32_e32 v39, v40
	v_mov_b32_e32 v36, v40
	v_mov_b32_e32 v37, v40
	s_waitcnt lgkmcnt(0)
	s_barrier
	v_mov_b32_e32 v202, v45
	v_add_u32_e32 v203, 0x11000, v44
	ds_read_b128 v[4:7], v202
	ds_read_b128 v[8:11], v203
	ds_read_b128 v[12:15], v203 offset:16
	ds_read_b128 v[16:19], v203 offset:32
	ds_read_b128 v[20:23], v203 offset:48
	ds_read_b128 v[24:27], v203 offset:1024
	ds_read_b128 v[28:31], v203 offset:1040
	ds_read_b128 v[32:35], v203 offset:1056
	ds_read_b128 v[88:91], v203 offset:1072
	s_waitcnt lgkmcnt(7)
	ds_read_b128 v[92:95], v203 offset:2048
	ds_read_b128 v[96:99], v203 offset:2064
	ds_read_b128 v[100:103], v203 offset:2080
	ds_read_b128 v[104:107], v203 offset:2096
	ds_read_b128 v[108:111], v203 offset:3072
	ds_read_b128 v[112:115], v203 offset:3088
	ds_read_b128 v[194:197], v203 offset:3104
	ds_read_b128 v[198:201], v203 offset:3120
.LBB0_94:
	s_waitcnt lgkmcnt(8)
	v_lshlrev_b32_e32 v64, 16, v4
	v_and_b32_e32 v65, 0xffff0000, v4
	v_lshlrev_b32_e32 v66, 16, v5
	v_and_b32_e32 v67, 0xffff0000, v5
	v_lshlrev_b32_e32 v68, 16, v6
	v_and_b32_e32 v69, 0xffff0000, v6
	v_lshlrev_b32_e32 v70, 16, v7
	v_and_b32_e32 v71, 0xffff0000, v7
	v_pk_mul_f32 v[46:47], v[10:11], v[64:65] op_sel:[0,1] op_sel_hi:[1,1]
	v_pk_mul_f32 v[48:49], v[14:15], v[66:67] op_sel:[0,1] op_sel_hi:[1,1]
	v_pk_mul_f32 v[50:51], v[18:19], v[68:69] op_sel:[0,1] op_sel_hi:[1,1]
	v_pk_mul_f32 v[52:53], v[22:23], v[70:71] op_sel:[0,1] op_sel_hi:[1,1]
	v_pk_mul_f32 v[54:55], v[26:27], v[64:65] op_sel:[0,1] op_sel_hi:[1,1]
	v_pk_mul_f32 v[56:57], v[30:31], v[66:67] op_sel:[0,1] op_sel_hi:[1,1]
	v_pk_mul_f32 v[58:59], v[34:35], v[68:69] op_sel:[0,1] op_sel_hi:[1,1]
	v_pk_mul_f32 v[60:61], v[90:91], v[70:71] op_sel:[0,1] op_sel_hi:[1,1]
	v_pk_fma_f32 v[46:47], v[8:9], v[64:65], v[46:47] op_sel_hi:[1,0,1]
	v_pk_fma_f32 v[48:49], v[12:13], v[66:67], v[48:49] op_sel_hi:[1,0,1]
	v_pk_fma_f32 v[50:51], v[16:17], v[68:69], v[50:51] op_sel_hi:[1,0,1]
	v_pk_fma_f32 v[52:53], v[20:21], v[70:71], v[52:53] op_sel_hi:[1,0,1]
	v_pk_fma_f32 v[54:55], v[24:25], v[64:65], v[54:55] op_sel_hi:[1,0,1]
	v_pk_fma_f32 v[56:57], v[28:29], v[66:67], v[56:57] op_sel_hi:[1,0,1]
	v_pk_fma_f32 v[58:59], v[32:33], v[68:69], v[58:59] op_sel_hi:[1,0,1]
	v_pk_fma_f32 v[60:61], v[88:89], v[70:71], v[60:61] op_sel_hi:[1,0,1]
	v_pk_add_f32 v[46:47], v[46:47], v[48:49]
	v_pk_add_f32 v[54:55], v[54:55], v[56:57]
	v_pk_add_f32 v[46:47], v[46:47], v[50:51]
	v_pk_add_f32 v[54:55], v[54:55], v[58:59]
	v_pk_add_f32 v[46:47], v[46:47], v[52:53]
	v_pk_add_f32 v[54:55], v[54:55], v[60:61]
	v_pk_add_f32 v[40:41], v[40:41], v[46:47]
	v_pk_add_f32 v[42:43], v[42:43], v[54:55]
	v_add_u32_e32 v202, 16, v202
	v_add_u32_e32 v203, 64, v203
	s_waitcnt lgkmcnt(0)
	ds_read_b128 v[4:7], v202
	ds_read_b128 v[8:11], v203
	ds_read_b128 v[12:15], v203 offset:16
	ds_read_b128 v[16:19], v203 offset:32
	ds_read_b128 v[20:23], v203 offset:48
	ds_read_b128 v[24:27], v203 offset:1024
	ds_read_b128 v[28:31], v203 offset:1040
	ds_read_b128 v[32:35], v203 offset:1056
	ds_read_b128 v[88:91], v203 offset:1072
	v_pk_mul_f32 v[46:47], v[94:95], v[64:65] op_sel:[0,1] op_sel_hi:[1,1]
	v_pk_mul_f32 v[48:49], v[98:99], v[66:67] op_sel:[0,1] op_sel_hi:[1,1]
	v_pk_mul_f32 v[50:51], v[102:103], v[68:69] op_sel:[0,1] op_sel_hi:[1,1]
	v_pk_mul_f32 v[52:53], v[106:107], v[70:71] op_sel:[0,1] op_sel_hi:[1,1]
	v_pk_mul_f32 v[54:55], v[110:111], v[64:65] op_sel:[0,1] op_sel_hi:[1,1]
	v_pk_mul_f32 v[56:57], v[114:115], v[66:67] op_sel:[0,1] op_sel_hi:[1,1]
	v_pk_mul_f32 v[58:59], v[196:197], v[68:69] op_sel:[0,1] op_sel_hi:[1,1]
	v_pk_mul_f32 v[60:61], v[200:201], v[70:71] op_sel:[0,1] op_sel_hi:[1,1]
	v_pk_fma_f32 v[46:47], v[92:93], v[64:65], v[46:47] op_sel_hi:[1,0,1]
	v_pk_fma_f32 v[48:49], v[96:97], v[66:67], v[48:49] op_sel_hi:[1,0,1]
	v_pk_fma_f32 v[50:51], v[100:101], v[68:69], v[50:51] op_sel_hi:[1,0,1]
	v_pk_fma_f32 v[52:53], v[104:105], v[70:71], v[52:53] op_sel_hi:[1,0,1]
	v_pk_fma_f32 v[54:55], v[108:109], v[64:65], v[54:55] op_sel_hi:[1,0,1]
	v_pk_fma_f32 v[56:57], v[112:113], v[66:67], v[56:57] op_sel_hi:[1,0,1]
	v_pk_fma_f32 v[58:59], v[194:195], v[68:69], v[58:59] op_sel_hi:[1,0,1]
	v_pk_fma_f32 v[60:61], v[198:199], v[70:71], v[60:61] op_sel_hi:[1,0,1]
	v_pk_add_f32 v[46:47], v[46:47], v[48:49]
	v_pk_add_f32 v[54:55], v[54:55], v[56:57]
	v_pk_add_f32 v[46:47], v[46:47], v[50:51]
	v_pk_add_f32 v[54:55], v[54:55], v[58:59]
	v_pk_add_f32 v[46:47], v[46:47], v[52:53]
	v_pk_add_f32 v[54:55], v[54:55], v[60:61]
	v_pk_add_f32 v[38:39], v[38:39], v[46:47]
	v_pk_add_f32 v[36:37], v[36:37], v[54:55]
	s_waitcnt lgkmcnt(7)
	ds_read_b128 v[92:95], v203 offset:2048
	ds_read_b128 v[96:99], v203 offset:2064
	ds_read_b128 v[100:103], v203 offset:2080
	ds_read_b128 v[104:107], v203 offset:2096
	ds_read_b128 v[108:111], v203 offset:3072
	ds_read_b128 v[112:115], v203 offset:3088
	ds_read_b128 v[194:197], v203 offset:3104
	ds_read_b128 v[198:201], v203 offset:3120
	s_add_i32 s0, s0, -1
	s_cmp_lg_u32 s0, 0
	s_cbranch_scc1 .LBB0_94
	v_swap_b32 v40, v41
	s_ashr_i32 s47, s8, 1
	v_cmp_gt_i32_e32 vcc, s47, v128
	s_nop 1
	v_cndmask_b32_e32 v40, v215, v40, vcc
	v_cmp_gt_i32_e32 vcc, s47, v1
	s_nop 1
	v_cndmask_b32_e32 v41, v215, v41, vcc
	v_cmp_gt_i32_e32 vcc, s47, v121
	ds_write2_b32 v184, v41, v40 offset1:1
	s_nop 0
	v_cndmask_b32_e32 v40, v215, v43, vcc
	v_cmp_gt_i32_e32 vcc, s47, v130
	s_nop 1
	v_cndmask_b32_e32 v41, v215, v42, vcc
	v_cmp_gt_i32_e32 vcc, s47, v129
	ds_write2_b32 v185, v41, v40 offset1:1
	s_nop 0
	v_cndmask_b32_e32 v39, v215, v39, vcc
	v_cmp_gt_i32_e32 vcc, s47, v132
	s_nop 1
	v_cndmask_b32_e32 v38, v215, v38, vcc
	v_cmp_gt_i32_e32 vcc, s47, v131
	ds_write2_b32 v186, v38, v39 offset1:1
	s_nop 0
	v_cndmask_b32_e32 v37, v215, v37, vcc
	v_cmp_gt_i32_e32 vcc, s47, v134
	s_nop 1
	v_cndmask_b32_e32 v36, v215, v36, vcc
	ds_write2_b32 v187, v36, v37 offset1:1
	s_waitcnt lgkmcnt(0)
	s_barrier
	s_and_saveexec_b64 s[0:1], s[4:5]
	s_cbranch_execz .LBB0_97
	ds_read2_b32 v[36:37], v191 offset1:1
	ds_read2_b32 v[38:39], v191 offset0:2 offset1:3
	ds_read2_b32 v[40:41], v191 offset0:4 offset1:5
	ds_read2_b32 v[42:43], v191 offset0:6 offset1:7
	ds_read2_b32 v[44:45], v191 offset0:8 offset1:9
	ds_read2_b32 v[46:47], v191 offset0:10 offset1:11
	ds_read2_b32 v[48:49], v191 offset0:12 offset1:13
	ds_read2_b32 v[50:51], v191 offset0:14 offset1:15
	ds_read2_b32 v[54:55], v191 offset0:16 offset1:17
	ds_read2_b32 v[56:57], v191 offset0:18 offset1:19
	ds_read2_b32 v[58:59], v191 offset0:20 offset1:21
	ds_read2_b32 v[60:61], v191 offset0:22 offset1:23
	ds_read2_b32 v[62:63], v191 offset0:24 offset1:25
	ds_read2_b32 v[64:65], v191 offset0:26 offset1:27
	ds_read2_b32 v[66:67], v191 offset0:28 offset1:29
	ds_read2_b32 v[68:69], v191 offset0:30 offset1:31
	s_waitcnt lgkmcnt(14)
	v_cmp_nlg_f32_e32 vcc, s73, v36
	s_nop 1
	v_cndmask_b32_e32 v70, v36, v215, vcc
	v_cndmask_b32_e64 v53, 0, -1, vcc
	v_cmp_gt_f32_e32 vcc, v37, v70
	s_nop 1
	v_cndmask_b32_e32 v70, v70, v37, vcc
	v_cndmask_b32_e64 v53, v53, 1, vcc
	v_cmp_gt_f32_e32 vcc, v38, v70
	s_nop 1
	v_cndmask_b32_e32 v70, v70, v38, vcc
	v_cndmask_b32_e64 v53, v53, 2, vcc
	v_cmp_gt_f32_e32 vcc, v39, v70
	s_nop 1
	v_cndmask_b32_e32 v70, v70, v39, vcc
	v_cndmask_b32_e64 v53, v53, 3, vcc
	s_waitcnt lgkmcnt(13)
	v_cmp_gt_f32_e32 vcc, v40, v70
	s_nop 1
	v_cndmask_b32_e32 v70, v70, v40, vcc
	v_cndmask_b32_e64 v53, v53, 4, vcc
	v_cmp_gt_f32_e32 vcc, v41, v70
	s_nop 1
	v_cndmask_b32_e32 v70, v70, v41, vcc
	v_cndmask_b32_e64 v53, v53, 5, vcc
	s_waitcnt lgkmcnt(12)
	v_cmp_gt_f32_e32 vcc, v42, v70
	s_nop 1
	v_cndmask_b32_e32 v70, v70, v42, vcc
	v_cndmask_b32_e64 v53, v53, 6, vcc
	v_cmp_gt_f32_e32 vcc, v43, v70
	s_nop 1
	v_cndmask_b32_e32 v70, v70, v43, vcc
	v_cndmask_b32_e64 v53, v53, 7, vcc
	s_waitcnt lgkmcnt(11)
	v_cmp_gt_f32_e32 vcc, v44, v70
	s_nop 1
	v_cndmask_b32_e32 v70, v70, v44, vcc
	v_cndmask_b32_e64 v53, v53, 8, vcc
	v_cmp_gt_f32_e32 vcc, v45, v70
	s_nop 1
	v_cndmask_b32_e32 v70, v70, v45, vcc
	v_cndmask_b32_e64 v53, v53, 9, vcc
	s_waitcnt lgkmcnt(10)
	v_cmp_gt_f32_e32 vcc, v46, v70
	s_nop 1
	v_cndmask_b32_e32 v70, v70, v46, vcc
	v_cndmask_b32_e64 v53, v53, 10, vcc
	v_cmp_gt_f32_e32 vcc, v47, v70
	s_nop 1
	v_cndmask_b32_e32 v70, v70, v47, vcc
	v_cndmask_b32_e64 v53, v53, 11, vcc
	s_waitcnt lgkmcnt(9)
	v_cmp_gt_f32_e32 vcc, v48, v70
	s_nop 1
	v_cndmask_b32_e32 v70, v70, v48, vcc
	v_cndmask_b32_e64 v53, v53, 12, vcc
	v_cmp_gt_f32_e32 vcc, v49, v70
	s_nop 1
	v_cndmask_b32_e32 v70, v70, v49, vcc
	v_cndmask_b32_e64 v53, v53, 13, vcc
	s_waitcnt lgkmcnt(8)
	v_cmp_gt_f32_e32 vcc, v50, v70
	s_nop 1
	v_cndmask_b32_e32 v70, v70, v50, vcc
	v_cndmask_b32_e64 v53, v53, 14, vcc
	v_cmp_gt_f32_e32 vcc, v51, v70
	s_nop 1
	v_cndmask_b32_e32 v70, v70, v51, vcc
	v_cndmask_b32_e64 v53, v53, 15, vcc
	s_waitcnt lgkmcnt(7)
	v_cmp_gt_f32_e32 vcc, v54, v70
	s_nop 1
	v_cndmask_b32_e32 v70, v70, v54, vcc
	v_cndmask_b32_e64 v53, v53, 16, vcc
	v_cmp_gt_f32_e32 vcc, v55, v70
	s_nop 1
	v_cndmask_b32_e32 v70, v70, v55, vcc
	v_cndmask_b32_e64 v53, v53, 17, vcc
	s_waitcnt lgkmcnt(6)
	v_cmp_gt_f32_e32 vcc, v56, v70
	s_nop 1
	v_cndmask_b32_e32 v70, v70, v56, vcc
	v_cndmask_b32_e64 v53, v53, 18, vcc
	v_cmp_gt_f32_e32 vcc, v57, v70
	s_nop 1
	v_cndmask_b32_e32 v70, v70, v57, vcc
	v_cndmask_b32_e64 v53, v53, 19, vcc
	s_waitcnt lgkmcnt(5)
	v_cmp_gt_f32_e32 vcc, v58, v70
	s_nop 1
	v_cndmask_b32_e32 v70, v70, v58, vcc
	v_cndmask_b32_e64 v53, v53, 20, vcc
	v_cmp_gt_f32_e32 vcc, v59, v70
	s_nop 1
	v_cndmask_b32_e32 v70, v70, v59, vcc
	v_cndmask_b32_e64 v53, v53, 21, vcc
	s_waitcnt lgkmcnt(4)
	v_cmp_gt_f32_e32 vcc, v60, v70
	s_nop 1
	v_cndmask_b32_e32 v70, v70, v60, vcc
	v_cndmask_b32_e64 v53, v53, 22, vcc
	v_cmp_gt_f32_e32 vcc, v61, v70
	s_nop 1
	v_cndmask_b32_e32 v70, v70, v61, vcc
	v_cndmask_b32_e64 v53, v53, 23, vcc
	s_waitcnt lgkmcnt(3)
	v_cmp_gt_f32_e32 vcc, v62, v70
	s_nop 1
	v_cndmask_b32_e32 v70, v70, v62, vcc
	v_cndmask_b32_e64 v53, v53, 24, vcc
	v_cmp_gt_f32_e32 vcc, v63, v70
	s_nop 1
	v_cndmask_b32_e32 v70, v70, v63, vcc
	v_cndmask_b32_e64 v53, v53, 25, vcc
	s_waitcnt lgkmcnt(2)
	v_cmp_gt_f32_e32 vcc, v64, v70
	s_nop 1
	v_cndmask_b32_e32 v70, v70, v64, vcc
	v_cndmask_b32_e64 v53, v53, 26, vcc
	v_cmp_gt_f32_e32 vcc, v65, v70
	s_nop 1
	v_cndmask_b32_e32 v70, v70, v65, vcc
	v_cndmask_b32_e64 v53, v53, 27, vcc
	s_waitcnt lgkmcnt(1)
	v_cmp_gt_f32_e32 vcc, v66, v70
	s_nop 1
	v_cndmask_b32_e32 v70, v70, v66, vcc
	v_cndmask_b32_e64 v53, v53, 28, vcc
	v_cmp_gt_f32_e32 vcc, v67, v70
	s_nop 1
	v_cndmask_b32_e32 v70, v70, v67, vcc
	v_cndmask_b32_e64 v53, v53, 29, vcc
	s_waitcnt lgkmcnt(0)
	v_cmp_gt_f32_e32 vcc, v68, v70
	s_nop 1
	v_cndmask_b32_e32 v70, v70, v68, vcc
	v_cndmask_b32_e64 v53, v53, 30, vcc
	v_cmp_ngt_f32_e32 vcc, v69, v70
	s_nop 1
	v_cndmask_b32_e32 v53, 31, v53, vcc
	v_lshlrev_b32_e64 v70, v53, 1
	v_cmp_lt_i32_e32 vcc, -1, v53
	s_nop 1
	v_cndmask_b32_e32 v70, 0, v70, vcc
	v_cmp_ne_u32_e32 vcc, 0, v53
	s_nop 1
	v_cndmask_b32_e32 v36, v215, v36, vcc
	v_cmp_ne_u32_e32 vcc, 1, v53
	s_nop 1
	v_cndmask_b32_e32 v37, v215, v37, vcc
	v_cmp_ne_u32_e32 vcc, 2, v53
	s_nop 1
	v_cndmask_b32_e32 v38, v215, v38, vcc
	v_cmp_ne_u32_e32 vcc, 3, v53
	s_nop 1
	v_cndmask_b32_e32 v39, v215, v39, vcc
	v_cmp_ne_u32_e32 vcc, 4, v53
	s_nop 1
	v_cndmask_b32_e32 v40, v215, v40, vcc
	v_cmp_ne_u32_e32 vcc, 5, v53
	s_nop 1
	v_cndmask_b32_e32 v41, v215, v41, vcc
	v_cmp_ne_u32_e32 vcc, 6, v53
	s_nop 1
	v_cndmask_b32_e32 v42, v215, v42, vcc
	v_cmp_ne_u32_e32 vcc, 7, v53
	s_nop 1
	v_cndmask_b32_e32 v43, v215, v43, vcc
	v_cmp_ne_u32_e32 vcc, 8, v53
	s_nop 1
	v_cndmask_b32_e32 v44, v215, v44, vcc
	v_cmp_ne_u32_e32 vcc, 9, v53
	s_nop 1
	v_cndmask_b32_e32 v45, v215, v45, vcc
	v_cmp_ne_u32_e32 vcc, 10, v53
	s_nop 1
	v_cndmask_b32_e32 v46, v215, v46, vcc
	v_cmp_ne_u32_e32 vcc, 11, v53
	s_nop 1
	v_cndmask_b32_e32 v47, v215, v47, vcc
	v_cmp_ne_u32_e32 vcc, 12, v53
	s_nop 1
	v_cndmask_b32_e32 v48, v215, v48, vcc
	v_cmp_ne_u32_e32 vcc, 13, v53
	s_nop 1
	v_cndmask_b32_e32 v49, v215, v49, vcc
	v_cmp_ne_u32_e32 vcc, 14, v53
	s_nop 1
	v_cndmask_b32_e32 v50, v215, v50, vcc
	v_cmp_ne_u32_e32 vcc, 15, v53
	s_nop 1
	v_cndmask_b32_e32 v51, v215, v51, vcc
	v_cmp_ne_u32_e32 vcc, 16, v53
	s_nop 1
	v_cndmask_b32_e32 v54, v215, v54, vcc
	v_cmp_ne_u32_e32 vcc, 17, v53
	s_nop 1
	v_cndmask_b32_e32 v55, v215, v55, vcc
	v_cmp_ne_u32_e32 vcc, 18, v53
	s_nop 1
	v_cndmask_b32_e32 v56, v215, v56, vcc
	v_cmp_ne_u32_e32 vcc, 19, v53
	s_nop 1
	v_cndmask_b32_e32 v57, v215, v57, vcc
	v_cmp_ne_u32_e32 vcc, 20, v53
	s_nop 1
	v_cndmask_b32_e32 v58, v215, v58, vcc
	v_cmp_ne_u32_e32 vcc, 21, v53
	s_nop 1
	v_cndmask_b32_e32 v59, v215, v59, vcc
	v_cmp_ne_u32_e32 vcc, 22, v53
	s_nop 1
	v_cndmask_b32_e32 v60, v215, v60, vcc
	v_cmp_ne_u32_e32 vcc, 23, v53
	s_nop 1
	v_cndmask_b32_e32 v61, v215, v61, vcc
	v_cmp_ne_u32_e32 vcc, 24, v53
	s_nop 1
	v_cndmask_b32_e32 v62, v215, v62, vcc
	v_cmp_ne_u32_e32 vcc, 25, v53
	s_nop 1
	v_cndmask_b32_e32 v63, v215, v63, vcc
	v_cmp_ne_u32_e32 vcc, 26, v53
	s_nop 1
	v_cndmask_b32_e32 v64, v215, v64, vcc
	v_cmp_ne_u32_e32 vcc, 27, v53
	s_nop 1
	v_cndmask_b32_e32 v65, v215, v65, vcc
	v_cmp_ne_u32_e32 vcc, 28, v53
	s_nop 1
	v_cndmask_b32_e32 v66, v215, v66, vcc
	v_cmp_ne_u32_e32 vcc, 29, v53
	s_nop 1
	v_cndmask_b32_e32 v67, v215, v67, vcc
	v_cmp_ne_u32_e32 vcc, 30, v53
	s_nop 1
	v_cndmask_b32_e32 v68, v215, v68, vcc
	v_cmp_ne_u32_e32 vcc, 31, v53
	s_nop 1
	v_cndmask_b32_e32 v53, v215, v69, vcc
	v_cmp_nlg_f32_e32 vcc, s73, v36
	v_lshl_or_b32 v69, 1, s47, v70
	s_nop 0
	v_cndmask_b32_e32 v71, v36, v215, vcc
	v_cndmask_b32_e64 v70, 0, -1, vcc
	v_cmp_gt_f32_e32 vcc, v37, v71
	s_nop 1
	v_cndmask_b32_e32 v71, v71, v37, vcc
	v_cndmask_b32_e64 v70, v70, 1, vcc
	v_cmp_gt_f32_e32 vcc, v38, v71
	s_nop 1
	v_cndmask_b32_e32 v71, v71, v38, vcc
	v_cndmask_b32_e64 v70, v70, 2, vcc
	v_cmp_gt_f32_e32 vcc, v39, v71
	s_nop 1
	v_cndmask_b32_e32 v71, v71, v39, vcc
	v_cndmask_b32_e64 v70, v70, 3, vcc
	v_cmp_gt_f32_e32 vcc, v40, v71
	s_nop 1
	v_cndmask_b32_e32 v71, v71, v40, vcc
	v_cndmask_b32_e64 v70, v70, 4, vcc
	v_cmp_gt_f32_e32 vcc, v41, v71
	s_nop 1
	v_cndmask_b32_e32 v71, v71, v41, vcc
	v_cndmask_b32_e64 v70, v70, 5, vcc
	v_cmp_gt_f32_e32 vcc, v42, v71
	s_nop 1
	v_cndmask_b32_e32 v71, v71, v42, vcc
	v_cndmask_b32_e64 v70, v70, 6, vcc
	v_cmp_gt_f32_e32 vcc, v43, v71
	s_nop 1
	v_cndmask_b32_e32 v71, v71, v43, vcc
	v_cndmask_b32_e64 v70, v70, 7, vcc
	v_cmp_gt_f32_e32 vcc, v44, v71
	s_nop 1
	v_cndmask_b32_e32 v71, v71, v44, vcc
	v_cndmask_b32_e64 v70, v70, 8, vcc
	v_cmp_gt_f32_e32 vcc, v45, v71
	s_nop 1
	v_cndmask_b32_e32 v71, v71, v45, vcc
	v_cndmask_b32_e64 v70, v70, 9, vcc
	v_cmp_gt_f32_e32 vcc, v46, v71
	s_nop 1
	v_cndmask_b32_e32 v71, v71, v46, vcc
	v_cndmask_b32_e64 v70, v70, 10, vcc
	v_cmp_gt_f32_e32 vcc, v47, v71
	s_nop 1
	v_cndmask_b32_e32 v71, v71, v47, vcc
	v_cndmask_b32_e64 v70, v70, 11, vcc
	v_cmp_gt_f32_e32 vcc, v48, v71
	s_nop 1
	v_cndmask_b32_e32 v71, v71, v48, vcc
	v_cndmask_b32_e64 v70, v70, 12, vcc
	v_cmp_gt_f32_e32 vcc, v49, v71
	s_nop 1
	v_cndmask_b32_e32 v71, v71, v49, vcc
	v_cndmask_b32_e64 v70, v70, 13, vcc
	v_cmp_gt_f32_e32 vcc, v50, v71
	s_nop 1
	v_cndmask_b32_e32 v71, v71, v50, vcc
	v_cndmask_b32_e64 v70, v70, 14, vcc
	v_cmp_gt_f32_e32 vcc, v51, v71
	s_nop 1
	v_cndmask_b32_e32 v71, v71, v51, vcc
	v_cndmask_b32_e64 v70, v70, 15, vcc
	v_cmp_gt_f32_e32 vcc, v54, v71
	s_nop 1
	v_cndmask_b32_e32 v71, v71, v54, vcc
	v_cndmask_b32_e64 v70, v70, 16, vcc
	v_cmp_gt_f32_e32 vcc, v55, v71
	s_nop 1
	v_cndmask_b32_e32 v71, v71, v55, vcc
	v_cndmask_b32_e64 v70, v70, 17, vcc
	v_cmp_gt_f32_e32 vcc, v56, v71
	s_nop 1
	v_cndmask_b32_e32 v71, v71, v56, vcc
	v_cndmask_b32_e64 v70, v70, 18, vcc
	v_cmp_gt_f32_e32 vcc, v57, v71
	s_nop 1
	v_cndmask_b32_e32 v71, v71, v57, vcc
	v_cndmask_b32_e64 v70, v70, 19, vcc
	v_cmp_gt_f32_e32 vcc, v58, v71
	s_nop 1
	v_cndmask_b32_e32 v71, v71, v58, vcc
	v_cndmask_b32_e64 v70, v70, 20, vcc
	v_cmp_gt_f32_e32 vcc, v59, v71
	s_nop 1
	v_cndmask_b32_e32 v71, v71, v59, vcc
	v_cndmask_b32_e64 v70, v70, 21, vcc
	v_cmp_gt_f32_e32 vcc, v60, v71
	s_nop 1
	v_cndmask_b32_e32 v71, v71, v60, vcc
	v_cndmask_b32_e64 v70, v70, 22, vcc
	v_cmp_gt_f32_e32 vcc, v61, v71
	s_nop 1
	v_cndmask_b32_e32 v71, v71, v61, vcc
	v_cndmask_b32_e64 v70, v70, 23, vcc
	v_cmp_gt_f32_e32 vcc, v62, v71
	s_nop 1
	v_cndmask_b32_e32 v71, v71, v62, vcc
	v_cndmask_b32_e64 v70, v70, 24, vcc
	v_cmp_gt_f32_e32 vcc, v63, v71
	s_nop 1
	v_cndmask_b32_e32 v71, v71, v63, vcc
	v_cndmask_b32_e64 v70, v70, 25, vcc
	v_cmp_gt_f32_e32 vcc, v64, v71
	s_nop 1
	v_cndmask_b32_e32 v71, v71, v64, vcc
	v_cndmask_b32_e64 v70, v70, 26, vcc
	v_cmp_gt_f32_e32 vcc, v65, v71
	s_nop 1
	v_cndmask_b32_e32 v71, v71, v65, vcc
	v_cndmask_b32_e64 v70, v70, 27, vcc
	v_cmp_gt_f32_e32 vcc, v66, v71
	s_nop 1
	v_cndmask_b32_e32 v71, v71, v66, vcc
	v_cndmask_b32_e64 v70, v70, 28, vcc
	v_cmp_gt_f32_e32 vcc, v67, v71
	s_nop 1
	v_cndmask_b32_e32 v71, v71, v67, vcc
	v_cndmask_b32_e64 v70, v70, 29, vcc
	v_cmp_gt_f32_e32 vcc, v68, v71
	s_nop 1
	v_cndmask_b32_e32 v71, v71, v68, vcc
	v_cndmask_b32_e64 v70, v70, 30, vcc
	v_cmp_ngt_f32_e32 vcc, v53, v71
	s_nop 1
	v_cndmask_b32_e32 v70, 31, v70, vcc
	v_lshlrev_b32_e64 v71, v70, 1
	v_cmp_lt_i32_e32 vcc, -1, v70
	s_nop 1
	v_cndmask_b32_e32 v71, 0, v71, vcc
	v_cmp_ne_u32_e32 vcc, 0, v70
	s_nop 1
	v_cndmask_b32_e32 v36, v215, v36, vcc
	v_cmp_ne_u32_e32 vcc, 1, v70
	s_nop 1
	v_cndmask_b32_e32 v37, v215, v37, vcc
	v_cmp_ne_u32_e32 vcc, 2, v70
	s_nop 1
	v_cndmask_b32_e32 v38, v215, v38, vcc
	v_cmp_ne_u32_e32 vcc, 3, v70
	s_nop 1
	v_cndmask_b32_e32 v39, v215, v39, vcc
	v_cmp_ne_u32_e32 vcc, 4, v70
	s_nop 1
	v_cndmask_b32_e32 v40, v215, v40, vcc
	v_cmp_ne_u32_e32 vcc, 5, v70
	s_nop 1
	v_cndmask_b32_e32 v41, v215, v41, vcc
	v_cmp_ne_u32_e32 vcc, 6, v70
	s_nop 1
	v_cndmask_b32_e32 v42, v215, v42, vcc
	v_cmp_ne_u32_e32 vcc, 7, v70
	s_nop 1
	v_cndmask_b32_e32 v43, v215, v43, vcc
	v_cmp_ne_u32_e32 vcc, 8, v70
	s_nop 1
	v_cndmask_b32_e32 v44, v215, v44, vcc
	v_cmp_ne_u32_e32 vcc, 9, v70
	s_nop 1
	v_cndmask_b32_e32 v45, v215, v45, vcc
	v_cmp_ne_u32_e32 vcc, 10, v70
	s_nop 1
	v_cndmask_b32_e32 v46, v215, v46, vcc
	v_cmp_ne_u32_e32 vcc, 11, v70
	s_nop 1
	v_cndmask_b32_e32 v47, v215, v47, vcc
	v_cmp_ne_u32_e32 vcc, 12, v70
	s_nop 1
	v_cndmask_b32_e32 v48, v215, v48, vcc
	v_cmp_ne_u32_e32 vcc, 13, v70
	s_nop 1
	v_cndmask_b32_e32 v49, v215, v49, vcc
	v_cmp_ne_u32_e32 vcc, 14, v70
	s_nop 1
	v_cndmask_b32_e32 v50, v215, v50, vcc
	v_cmp_ne_u32_e32 vcc, 15, v70
	s_nop 1
	v_cndmask_b32_e32 v51, v215, v51, vcc
	v_cmp_ne_u32_e32 vcc, 16, v70
	s_nop 1
	v_cndmask_b32_e32 v54, v215, v54, vcc
	v_cmp_ne_u32_e32 vcc, 17, v70
	s_nop 1
	v_cndmask_b32_e32 v55, v215, v55, vcc
	v_cmp_ne_u32_e32 vcc, 18, v70
	s_nop 1
	v_cndmask_b32_e32 v56, v215, v56, vcc
	v_cmp_ne_u32_e32 vcc, 19, v70
	s_nop 1
	v_cndmask_b32_e32 v57, v215, v57, vcc
	v_cmp_ne_u32_e32 vcc, 20, v70
	s_nop 1
	v_cndmask_b32_e32 v58, v215, v58, vcc
	v_cmp_ne_u32_e32 vcc, 21, v70
	s_nop 1
	v_cndmask_b32_e32 v59, v215, v59, vcc
	v_cmp_ne_u32_e32 vcc, 22, v70
	s_nop 1
	v_cndmask_b32_e32 v60, v215, v60, vcc
	v_cmp_ne_u32_e32 vcc, 23, v70
	s_nop 1
	v_cndmask_b32_e32 v61, v215, v61, vcc
	v_cmp_ne_u32_e32 vcc, 24, v70
	s_nop 1
	v_cndmask_b32_e32 v62, v215, v62, vcc
	v_cmp_ne_u32_e32 vcc, 25, v70
	s_nop 1
	v_cndmask_b32_e32 v63, v215, v63, vcc
	v_cmp_ne_u32_e32 vcc, 26, v70
	s_nop 1
	v_cndmask_b32_e32 v64, v215, v64, vcc
	v_cmp_ne_u32_e32 vcc, 27, v70
	s_nop 1
	v_cndmask_b32_e32 v65, v215, v65, vcc
	v_cmp_ne_u32_e32 vcc, 28, v70
	s_nop 1
	v_cndmask_b32_e32 v66, v215, v66, vcc
	v_cmp_ne_u32_e32 vcc, 29, v70
	s_nop 1
	v_cndmask_b32_e32 v67, v215, v67, vcc
	v_cmp_ne_u32_e32 vcc, 30, v70
	s_nop 1
	v_cndmask_b32_e32 v68, v215, v68, vcc
	v_cmp_ne_u32_e32 vcc, 31, v70
	s_nop 1
	v_cndmask_b32_e32 v53, v215, v53, vcc
	v_cmp_nlg_f32_e32 vcc, s73, v36
	s_nop 1
	v_cndmask_b32_e32 v36, v36, v215, vcc
	v_cndmask_b32_e64 v70, 0, -1, vcc
	v_cmp_gt_f32_e32 vcc, v37, v36
	s_nop 1
	v_cndmask_b32_e32 v36, v36, v37, vcc
	v_cndmask_b32_e64 v70, v70, 1, vcc
	v_cmp_gt_f32_e32 vcc, v38, v36
	s_nop 1
	v_cndmask_b32_e32 v36, v36, v38, vcc
	v_cndmask_b32_e64 v37, v70, 2, vcc
	v_cmp_gt_f32_e32 vcc, v39, v36
	s_nop 1
	v_cndmask_b32_e32 v36, v36, v39, vcc
	v_cndmask_b32_e64 v37, v37, 3, vcc
	v_cmp_gt_f32_e32 vcc, v40, v36
	s_nop 1
	v_cndmask_b32_e32 v36, v36, v40, vcc
	v_cndmask_b32_e64 v37, v37, 4, vcc
	v_cmp_gt_f32_e32 vcc, v41, v36
	s_nop 1
	v_cndmask_b32_e32 v36, v36, v41, vcc
	v_cndmask_b32_e64 v37, v37, 5, vcc
	v_cmp_gt_f32_e32 vcc, v42, v36
	s_nop 1
	v_cndmask_b32_e32 v36, v36, v42, vcc
	v_cndmask_b32_e64 v37, v37, 6, vcc
	v_cmp_gt_f32_e32 vcc, v43, v36
	s_nop 1
	v_cndmask_b32_e32 v36, v36, v43, vcc
	v_cndmask_b32_e64 v37, v37, 7, vcc
	v_cmp_gt_f32_e32 vcc, v44, v36
	s_nop 1
	v_cndmask_b32_e32 v36, v36, v44, vcc
	v_cndmask_b32_e64 v37, v37, 8, vcc
	v_cmp_gt_f32_e32 vcc, v45, v36
	s_nop 1
	v_cndmask_b32_e32 v36, v36, v45, vcc
	v_cndmask_b32_e64 v37, v37, 9, vcc
	v_cmp_gt_f32_e32 vcc, v46, v36
	s_nop 1
	v_cndmask_b32_e32 v36, v36, v46, vcc
	v_cndmask_b32_e64 v37, v37, 10, vcc
	v_cmp_gt_f32_e32 vcc, v47, v36
	s_nop 1
	v_cndmask_b32_e32 v36, v36, v47, vcc
	v_cndmask_b32_e64 v37, v37, 11, vcc
	v_cmp_gt_f32_e32 vcc, v48, v36
	s_nop 1
	v_cndmask_b32_e32 v36, v36, v48, vcc
	v_cndmask_b32_e64 v37, v37, 12, vcc
	v_cmp_gt_f32_e32 vcc, v49, v36
	s_nop 1
	v_cndmask_b32_e32 v36, v36, v49, vcc
	v_cndmask_b32_e64 v37, v37, 13, vcc
	v_cmp_gt_f32_e32 vcc, v50, v36
	s_nop 1
	v_cndmask_b32_e32 v36, v36, v50, vcc
	v_cndmask_b32_e64 v37, v37, 14, vcc
	v_cmp_gt_f32_e32 vcc, v51, v36
	s_nop 1
	v_cndmask_b32_e32 v36, v36, v51, vcc
	v_cndmask_b32_e64 v37, v37, 15, vcc
	v_cmp_gt_f32_e32 vcc, v54, v36
	s_nop 1
	v_cndmask_b32_e32 v36, v36, v54, vcc
	v_cndmask_b32_e64 v37, v37, 16, vcc
	v_cmp_gt_f32_e32 vcc, v55, v36
	s_nop 1
	v_cndmask_b32_e32 v36, v36, v55, vcc
	v_cndmask_b32_e64 v37, v37, 17, vcc
	v_cmp_gt_f32_e32 vcc, v56, v36
	s_nop 1
	v_cndmask_b32_e32 v36, v36, v56, vcc
	v_cndmask_b32_e64 v37, v37, 18, vcc
	v_cmp_gt_f32_e32 vcc, v57, v36
	s_nop 1
	v_cndmask_b32_e32 v36, v36, v57, vcc
	v_cndmask_b32_e64 v37, v37, 19, vcc
	v_cmp_gt_f32_e32 vcc, v58, v36
	s_nop 1
	v_cndmask_b32_e32 v36, v36, v58, vcc
	v_cndmask_b32_e64 v37, v37, 20, vcc
	v_cmp_gt_f32_e32 vcc, v59, v36
	s_nop 1
	v_cndmask_b32_e32 v36, v36, v59, vcc
	v_cndmask_b32_e64 v37, v37, 21, vcc
	v_cmp_gt_f32_e32 vcc, v60, v36
	s_nop 1
	v_cndmask_b32_e32 v36, v36, v60, vcc
	v_cndmask_b32_e64 v37, v37, 22, vcc
	v_cmp_gt_f32_e32 vcc, v61, v36
	s_nop 1
	v_cndmask_b32_e32 v36, v36, v61, vcc
	v_cndmask_b32_e64 v37, v37, 23, vcc
	v_cmp_gt_f32_e32 vcc, v62, v36
	s_nop 1
	v_cndmask_b32_e32 v36, v36, v62, vcc
	v_cndmask_b32_e64 v37, v37, 24, vcc
	v_cmp_gt_f32_e32 vcc, v63, v36
	s_nop 1
	v_cndmask_b32_e32 v36, v36, v63, vcc
	v_cndmask_b32_e64 v37, v37, 25, vcc
	v_cmp_gt_f32_e32 vcc, v64, v36
	s_nop 1
	v_cndmask_b32_e32 v36, v36, v64, vcc
	v_cndmask_b32_e64 v37, v37, 26, vcc
	v_cmp_gt_f32_e32 vcc, v65, v36
	s_nop 1
	v_cndmask_b32_e32 v36, v36, v65, vcc
	v_cndmask_b32_e64 v37, v37, 27, vcc
	v_cmp_gt_f32_e32 vcc, v66, v36
	s_nop 1
	v_cndmask_b32_e32 v36, v36, v66, vcc
	v_cndmask_b32_e64 v37, v37, 28, vcc
	v_cmp_gt_f32_e32 vcc, v67, v36
	s_nop 1
	v_cndmask_b32_e32 v36, v36, v67, vcc
	v_cndmask_b32_e64 v37, v37, 29, vcc
	v_cmp_gt_f32_e32 vcc, v68, v36
	s_nop 1
	v_cndmask_b32_e32 v36, v36, v68, vcc
	v_cndmask_b32_e64 v37, v37, 30, vcc
	v_cmp_ngt_f32_e32 vcc, v53, v36
	s_nop 1
	v_cndmask_b32_e32 v36, 31, v37, vcc
	v_lshlrev_b32_e64 v37, v36, 1
	v_cmp_lt_i32_e32 vcc, -1, v36
	s_nop 1
	v_cndmask_b32_e32 v36, 0, v37, vcc
	v_or3_b32 v36, v69, v71, v36
	ds_write_b32 v166, v36
